# grid barrier: the releasing leader no longer relays through the per-XCD word nor waits for its release atomics before the closing barrier
# baseline (speedup 1.0000x reference)
.LBB0_121:
	s_or_b64 exec, exec, s[6:7]
	v_mov_b32_e32 v0, 0x2000
	v_mov_b32_e32 v1, 1
	s_nop 0
